# ff1 GEMM epilogue: bf16 column groups paired with v_permlane16_swap and stored 16 B per lane (half the store instructions); on top of the attention MFMA-gap scheduling and GDN solve rewrite
# speedup vs baseline: 1.0231x; 1.0065x over previous
; DI unsigned cvtpk(float lo, float hi) { f32x2_t v = {lo, hi}; bf16x2_t b = __builtin_convertvector(v, bf16x2_t); return __builtin_bit_cast(unsigned, b); }
; DI float frsq_(float x) { return __builtin_amdgcn_rsqf(x); }
;     DI void operator()(const f32x4 (&acc)[2][2][4][2], const Unit& u, int wr, int wc, int fr, int fq) const {
;         const int row0 = u.pm * BM + wr * 64 + fr, col0 = u.pn * BM + wc * 32 + 4 * fq;
; #pragma unroll
;         for (int ai = 0; ai < 2; ++ai)
; #pragma unroll
;             for (int m = 0; m < 4; ++m) { bf16_t* rp = O + (size_t)(row0 + ai * HALF + m * 16) * ldc + col0;
;                 float rsc = 1.f; if (RSCALE) rsc = frsq_(rss[row0 + ai * HALF + m * 16] * (1.f / 2048.f) + EPS);
; #pragma unroll
;                 for (int bj = 0; bj < 2; ++bj)
; #pragma unroll
;                     for (int n = 0; n < 2; ++n) { f32x4 v = acc[ai][bj][m][n]; if (RSCALE) v = v * rsc;
;                         if (ACT == 1) {
; #pragma unroll
;                             for (int j = 0; j < 4; ++j) { const float r = v[j] > 0.f ? v[j] : 0.f; v[j] = r * r; } }
;                         u32x2 w; w.x = cvtpk(v[0], v[1]); w.y = cvtpk(v[2], v[3]); *(u32x2*)(rp + bj * HALF + n * 16) = w; } }
;     }
.LBB0_1393:
	v_lshl_add_u32 v144, s64, 8, v148
	v_ashrrev_i32_e32 v145, 31, v144
	v_lshl_add_u64 v[140:141], v[144:145], 2, s[10:11]
	global_load_dword v155, v[140:141], off
	v_lshl_or_b32 v142, s63, 8, v150
	v_ashrrev_i32_e32 v143, 31, v142
	v_lshlrev_b64 v[146:147], 1, v[142:143]
	v_mbcnt_lo_u32_b32 v171, -1, 0
	v_mbcnt_hi_u32_b32 v171, -1, v171
	v_and_b32_e32 v171, 16, v171
	v_lshrrev_b32_e32 v172, 1, v171
	v_add_u32_e32 v171, v171, v172
	v_add_u32_e32 v146, v146, v171
	v_lshlrev_b64 v[158:159], 14, v[144:145]
	v_or_b32_e32 v156, 16, v144
	v_ashrrev_i32_e32 v157, 31, v156
	s_waitcnt vmcnt(0)
	v_fmamk_f32 v142, v155, 0x3a000000, v154
	v_rsq_f32_e32 v160, v142
	v_lshl_add_u64 v[142:143], s[8:9], 0, v[158:159]
	v_lshl_add_u64 v[142:143], v[142:143], 0, v[146:147]
	v_lshl_add_u64 v[158:159], v[156:157], 2, s[10:11]
	v_pk_mul_f32 v[126:127], v[126:127], v[160:161] op_sel_hi:[1,0]
	v_pk_mul_f32 v[124:125], v[124:125], v[160:161] op_sel_hi:[1,0]
	v_pk_mul_f32 v[122:123], v[122:123], v[160:161] op_sel_hi:[1,0]
	v_pk_mul_f32 v[120:121], v[120:121], v[160:161] op_sel_hi:[1,0]
	v_pk_mul_f32 v[118:119], v[118:119], v[160:161] op_sel_hi:[1,0]
	v_pk_mul_f32 v[116:117], v[116:117], v[160:161] op_sel_hi:[1,0]
	v_pk_mul_f32 v[114:115], v[114:115], v[160:161] op_sel_hi:[1,0]
	v_pk_mul_f32 v[112:113], v[112:113], v[160:161] op_sel_hi:[1,0]
	v_max_f32_e32 v125, 0, v125
	v_max_f32_e32 v124, 0, v124
	v_max_f32_e32 v127, 0, v127
	v_max_f32_e32 v126, 0, v126
	v_max_f32_e32 v121, 0, v121
	v_max_f32_e32 v120, 0, v120
	v_max_f32_e32 v123, 0, v123
	v_max_f32_e32 v122, 0, v122
	v_max_f32_e32 v117, 0, v117
	v_max_f32_e32 v116, 0, v116
	v_max_f32_e32 v119, 0, v119
	v_max_f32_e32 v118, 0, v118
	v_max_f32_e32 v113, 0, v113
	v_max_f32_e32 v112, 0, v112
	v_max_f32_e32 v115, 0, v115
	v_max_f32_e32 v114, 0, v114
	v_pk_mul_f32 v[124:125], v[124:125], v[124:125]
	v_pk_mul_f32 v[126:127], v[126:127], v[126:127]
	v_pk_mul_f32 v[120:121], v[120:121], v[120:121]
	v_pk_mul_f32 v[122:123], v[122:123], v[122:123]
	v_pk_mul_f32 v[116:117], v[116:117], v[116:117]
	v_pk_mul_f32 v[118:119], v[118:119], v[118:119]
	v_pk_mul_f32 v[112:113], v[112:113], v[112:113]
	v_pk_mul_f32 v[114:115], v[114:115], v[114:115]
	v_cvt_pk_bf16_f32 v123, v122, v123
	v_cvt_pk_bf16_f32 v122, v120, v121
	v_cvt_pk_bf16_f32 v120, v124, v125
	v_cvt_pk_bf16_f32 v121, v126, v127
	v_cvt_pk_bf16_f32 v115, v114, v115
	v_cvt_pk_bf16_f32 v114, v112, v113
	v_cvt_pk_bf16_f32 v112, v116, v117
	v_cvt_pk_bf16_f32 v113, v118, v119
	s_nop 1
	v_permlane16_swap_b32_e32 v120, v122
	v_permlane16_swap_b32_e32 v121, v123
	v_permlane16_swap_b32_e32 v112, v114
	v_permlane16_swap_b32_e32 v113, v115
	global_store_dwordx4 v[142:143], v[120:123], off
	global_store_dwordx4 v[142:143], v[112:115], off offset:256
	s_nop 1
	global_load_dword v116, v[158:159], off
	v_lshlrev_b64 v[114:115], 14, v[156:157]
	v_or_b32_e32 v112, 32, v144
	v_lshl_add_u64 v[114:115], s[8:9], 0, v[114:115]
	v_ashrrev_i32_e32 v113, 31, v112
	v_lshl_add_u64 v[114:115], v[114:115], 0, v[146:147]
	v_lshl_add_u64 v[118:119], v[112:113], 2, s[10:11]
	s_waitcnt vmcnt(0)
	v_fmamk_f32 v116, v116, 0x3a000000, v154
	v_rsq_f32_e32 v116, v116
	s_nop 0
	v_pk_mul_f32 v[110:111], v[110:111], v[116:117] op_sel_hi:[1,0]
	v_pk_mul_f32 v[108:109], v[108:109], v[116:117] op_sel_hi:[1,0]
	v_pk_mul_f32 v[106:107], v[106:107], v[116:117] op_sel_hi:[1,0]
	v_pk_mul_f32 v[104:105], v[104:105], v[116:117] op_sel_hi:[1,0]
	v_pk_mul_f32 v[102:103], v[102:103], v[116:117] op_sel_hi:[1,0]
	v_pk_mul_f32 v[100:101], v[100:101], v[116:117] op_sel_hi:[1,0]
	v_pk_mul_f32 v[98:99], v[98:99], v[116:117] op_sel_hi:[1,0]
	v_pk_mul_f32 v[96:97], v[96:97], v[116:117] op_sel_hi:[1,0]
	v_max_f32_e32 v109, 0, v109
	v_max_f32_e32 v108, 0, v108
	v_max_f32_e32 v111, 0, v111
	v_max_f32_e32 v110, 0, v110
	v_max_f32_e32 v105, 0, v105
	v_max_f32_e32 v104, 0, v104
	v_max_f32_e32 v107, 0, v107
	v_max_f32_e32 v106, 0, v106
	v_max_f32_e32 v101, 0, v101
	v_max_f32_e32 v100, 0, v100
	v_max_f32_e32 v103, 0, v103
	v_max_f32_e32 v102, 0, v102
	v_max_f32_e32 v97, 0, v97
	v_max_f32_e32 v96, 0, v96
	v_max_f32_e32 v99, 0, v99
	v_max_f32_e32 v98, 0, v98
	v_pk_mul_f32 v[108:109], v[108:109], v[108:109]
	v_pk_mul_f32 v[110:111], v[110:111], v[110:111]
	v_pk_mul_f32 v[104:105], v[104:105], v[104:105]
	v_pk_mul_f32 v[106:107], v[106:107], v[106:107]
	v_pk_mul_f32 v[100:101], v[100:101], v[100:101]
	v_pk_mul_f32 v[102:103], v[102:103], v[102:103]
	v_pk_mul_f32 v[96:97], v[96:97], v[96:97]
	v_pk_mul_f32 v[98:99], v[98:99], v[98:99]
	v_cvt_pk_bf16_f32 v107, v106, v107
	v_cvt_pk_bf16_f32 v106, v104, v105
	v_cvt_pk_bf16_f32 v104, v108, v109
	v_cvt_pk_bf16_f32 v105, v110, v111
	v_cvt_pk_bf16_f32 v99, v98, v99
	v_cvt_pk_bf16_f32 v98, v96, v97
	v_cvt_pk_bf16_f32 v96, v100, v101
	v_cvt_pk_bf16_f32 v97, v102, v103
	s_nop 1
	v_permlane16_swap_b32_e32 v104, v106
	v_permlane16_swap_b32_e32 v105, v107
	v_permlane16_swap_b32_e32 v96, v98
	v_permlane16_swap_b32_e32 v97, v99
	global_store_dwordx4 v[114:115], v[104:107], off
	global_store_dwordx4 v[114:115], v[96:99], off offset:256
	s_nop 1
	global_load_dword v100, v[118:119], off
	v_lshlrev_b64 v[98:99], 14, v[112:113]
	v_or_b32_e32 v96, 48, v144
	v_lshl_add_u64 v[98:99], s[8:9], 0, v[98:99]
	v_ashrrev_i32_e32 v97, 31, v96
	v_lshl_add_u64 v[98:99], v[98:99], 0, v[146:147]
	v_lshl_add_u64 v[102:103], v[96:97], 2, s[10:11]
	s_waitcnt vmcnt(0)
; DI unsigned cvtpk(float lo, float hi) { f32x2_t v = {lo, hi}; bf16x2_t b = __builtin_convertvector(v, bf16x2_t); return __builtin_bit_cast(unsigned, b); }
; DI float frsq_(float x) { return __builtin_amdgcn_rsqf(x); }
;     DI void operator()(const f32x4 (&acc)[2][2][4][2], const Unit& u, int wr, int wc, int fr, int fq) const {
;         const int row0 = u.pm * BM + wr * 64 + fr, col0 = u.pn * BM + wc * 32 + 4 * fq;
; #pragma unroll
;         for (int ai = 0; ai < 2; ++ai)
; #pragma unroll
;             for (int m = 0; m < 4; ++m) { bf16_t* rp = O + (size_t)(row0 + ai * HALF + m * 16) * ldc + col0;
;                 float rsc = 1.f; if (RSCALE) rsc = frsq_(rss[row0 + ai * HALF + m * 16] * (1.f / 2048.f) + EPS);
; #pragma unroll
;                 for (int bj = 0; bj < 2; ++bj)
; #pragma unroll
;                     for (int n = 0; n < 2; ++n) { f32x4 v = acc[ai][bj][m][n]; if (RSCALE) v = v * rsc;
;                         if (ACT == 1) {
; #pragma unroll
;                             for (int j = 0; j < 4; ++j) { const float r = v[j] > 0.f ? v[j] : 0.f; v[j] = r * r; } }
;                         u32x2 w; w.x = cvtpk(v[0], v[1]); w.y = cvtpk(v[2], v[3]); *(u32x2*)(rp + bj * HALF + n * 16) = w; } }
;     }
	v_fmamk_f32 v100, v100, 0x3a000000, v154
	v_rsq_f32_e32 v100, v100
	s_nop 0
	v_pk_mul_f32 v[94:95], v[94:95], v[100:101] op_sel_hi:[1,0]
	v_pk_mul_f32 v[92:93], v[92:93], v[100:101] op_sel_hi:[1,0]
	v_pk_mul_f32 v[90:91], v[90:91], v[100:101] op_sel_hi:[1,0]
	v_pk_mul_f32 v[88:89], v[88:89], v[100:101] op_sel_hi:[1,0]
	v_pk_mul_f32 v[86:87], v[86:87], v[100:101] op_sel_hi:[1,0]
	v_pk_mul_f32 v[84:85], v[84:85], v[100:101] op_sel_hi:[1,0]
	v_pk_mul_f32 v[82:83], v[82:83], v[100:101] op_sel_hi:[1,0]
	v_pk_mul_f32 v[80:81], v[80:81], v[100:101] op_sel_hi:[1,0]
	v_max_f32_e32 v93, 0, v93
	v_max_f32_e32 v92, 0, v92
	v_max_f32_e32 v95, 0, v95
	v_max_f32_e32 v94, 0, v94
	v_max_f32_e32 v89, 0, v89
	v_max_f32_e32 v88, 0, v88
	v_max_f32_e32 v91, 0, v91
	v_max_f32_e32 v90, 0, v90
	v_max_f32_e32 v85, 0, v85
	v_max_f32_e32 v84, 0, v84
	v_max_f32_e32 v87, 0, v87
	v_max_f32_e32 v86, 0, v86
	v_max_f32_e32 v81, 0, v81
	v_max_f32_e32 v80, 0, v80
	v_max_f32_e32 v83, 0, v83
	v_max_f32_e32 v82, 0, v82
	v_pk_mul_f32 v[92:93], v[92:93], v[92:93]
	v_pk_mul_f32 v[94:95], v[94:95], v[94:95]
	v_pk_mul_f32 v[88:89], v[88:89], v[88:89]
	v_pk_mul_f32 v[90:91], v[90:91], v[90:91]
	v_pk_mul_f32 v[84:85], v[84:85], v[84:85]
	v_pk_mul_f32 v[86:87], v[86:87], v[86:87]
	v_pk_mul_f32 v[80:81], v[80:81], v[80:81]
	v_pk_mul_f32 v[82:83], v[82:83], v[82:83]
	v_cvt_pk_bf16_f32 v91, v90, v91
	v_cvt_pk_bf16_f32 v90, v88, v89
	v_cvt_pk_bf16_f32 v88, v92, v93
	v_cvt_pk_bf16_f32 v89, v94, v95
	v_cvt_pk_bf16_f32 v83, v82, v83
	v_cvt_pk_bf16_f32 v82, v80, v81
	v_cvt_pk_bf16_f32 v80, v84, v85
	v_cvt_pk_bf16_f32 v81, v86, v87
	s_nop 1
	v_permlane16_swap_b32_e32 v88, v90
	v_permlane16_swap_b32_e32 v89, v91
	v_permlane16_swap_b32_e32 v80, v82
	v_permlane16_swap_b32_e32 v81, v83
	global_store_dwordx4 v[98:99], v[88:91], off
	global_store_dwordx4 v[98:99], v[80:83], off offset:256
	s_nop 1
	global_load_dword v80, v[102:103], off
	v_lshlrev_b64 v[82:83], 14, v[96:97]
	v_lshl_add_u64 v[82:83], s[8:9], 0, v[82:83]
	v_lshl_add_u64 v[82:83], v[82:83], 0, v[146:147]
	s_waitcnt vmcnt(0)
	v_fmamk_f32 v80, v80, 0x3a000000, v154
	v_rsq_f32_e32 v80, v80
	s_nop 0
	v_pk_mul_f32 v[78:79], v[78:79], v[80:81] op_sel_hi:[1,0]
	v_pk_mul_f32 v[76:77], v[76:77], v[80:81] op_sel_hi:[1,0]
	v_pk_mul_f32 v[74:75], v[74:75], v[80:81] op_sel_hi:[1,0]
	v_pk_mul_f32 v[72:73], v[72:73], v[80:81] op_sel_hi:[1,0]
	v_pk_mul_f32 v[70:71], v[70:71], v[80:81] op_sel_hi:[1,0]
	v_pk_mul_f32 v[68:69], v[68:69], v[80:81] op_sel_hi:[1,0]
	v_pk_mul_f32 v[66:67], v[66:67], v[80:81] op_sel_hi:[1,0]
	v_pk_mul_f32 v[64:65], v[64:65], v[80:81] op_sel_hi:[1,0]
	v_max_f32_e32 v77, 0, v77
	v_max_f32_e32 v76, 0, v76
	v_max_f32_e32 v79, 0, v79
	v_max_f32_e32 v78, 0, v78
	v_max_f32_e32 v73, 0, v73
	v_max_f32_e32 v72, 0, v72
	v_max_f32_e32 v75, 0, v75
	v_max_f32_e32 v74, 0, v74
	v_max_f32_e32 v69, 0, v69
	v_max_f32_e32 v68, 0, v68
	v_max_f32_e32 v71, 0, v71
	v_max_f32_e32 v70, 0, v70
	v_max_f32_e32 v65, 0, v65
	v_max_f32_e32 v64, 0, v64
	v_max_f32_e32 v67, 0, v67
	v_max_f32_e32 v66, 0, v66
	v_pk_mul_f32 v[76:77], v[76:77], v[76:77]
	v_pk_mul_f32 v[78:79], v[78:79], v[78:79]
	v_pk_mul_f32 v[72:73], v[72:73], v[72:73]
	v_pk_mul_f32 v[74:75], v[74:75], v[74:75]
	v_pk_mul_f32 v[68:69], v[68:69], v[68:69]
	v_pk_mul_f32 v[70:71], v[70:71], v[70:71]
	v_pk_mul_f32 v[64:65], v[64:65], v[64:65]
	v_pk_mul_f32 v[66:67], v[66:67], v[66:67]
	v_cvt_pk_bf16_f32 v75, v74, v75
	v_cvt_pk_bf16_f32 v74, v72, v73
	v_cvt_pk_bf16_f32 v72, v76, v77
	v_cvt_pk_bf16_f32 v73, v78, v79
	v_cvt_pk_bf16_f32 v67, v66, v67
	v_cvt_pk_bf16_f32 v66, v64, v65
	v_cvt_pk_bf16_f32 v64, v68, v69
	v_cvt_pk_bf16_f32 v65, v70, v71
	s_nop 1
	v_permlane16_swap_b32_e32 v72, v74
	v_permlane16_swap_b32_e32 v73, v75
	v_permlane16_swap_b32_e32 v64, v66
	v_permlane16_swap_b32_e32 v65, v67
	global_store_dwordx4 v[82:83], v[72:75], off
	global_store_dwordx4 v[82:83], v[64:67], off offset:256
	s_nop 1
	global_load_dword v66, v[140:141], off offset:512
	v_add_co_u32_e32 v68, vcc, s59, v142
	v_lshl_add_u64 v[64:65], v[142:143], 0, s[16:17]
	s_nop 0
	v_addc_co_u32_e32 v69, vcc, 0, v143, vcc
	s_waitcnt vmcnt(0)
	v_fmamk_f32 v66, v66, 0x3a000000, v154
	v_rsq_f32_e32 v66, v66
	s_nop 0
	v_pk_mul_f32 v[62:63], v[62:63], v[66:67] op_sel_hi:[1,0]
	v_pk_mul_f32 v[60:61], v[60:61], v[66:67] op_sel_hi:[1,0]
	v_pk_mul_f32 v[58:59], v[58:59], v[66:67] op_sel_hi:[1,0]
	v_pk_mul_f32 v[56:57], v[56:57], v[66:67] op_sel_hi:[1,0]
	v_pk_mul_f32 v[54:55], v[54:55], v[66:67] op_sel_hi:[1,0]
	v_pk_mul_f32 v[52:53], v[52:53], v[66:67] op_sel_hi:[1,0]
	v_pk_mul_f32 v[50:51], v[50:51], v[66:67] op_sel_hi:[1,0]
	v_pk_mul_f32 v[48:49], v[48:49], v[66:67] op_sel_hi:[1,0]
	v_max_f32_e32 v61, 0, v61
	v_max_f32_e32 v60, 0, v60
	v_max_f32_e32 v63, 0, v63
	v_max_f32_e32 v62, 0, v62
	v_max_f32_e32 v57, 0, v57
	v_max_f32_e32 v56, 0, v56
	v_max_f32_e32 v59, 0, v59
	v_max_f32_e32 v58, 0, v58
	v_max_f32_e32 v53, 0, v53
	v_max_f32_e32 v52, 0, v52
	v_max_f32_e32 v55, 0, v55
	v_max_f32_e32 v54, 0, v54
	v_max_f32_e32 v49, 0, v49
	v_max_f32_e32 v48, 0, v48
	v_max_f32_e32 v51, 0, v51
	v_max_f32_e32 v50, 0, v50
	v_pk_mul_f32 v[60:61], v[60:61], v[60:61]
	v_pk_mul_f32 v[62:63], v[62:63], v[62:63]
	v_pk_mul_f32 v[56:57], v[56:57], v[56:57]
	v_pk_mul_f32 v[58:59], v[58:59], v[58:59]
	v_pk_mul_f32 v[52:53], v[52:53], v[52:53]
	v_pk_mul_f32 v[54:55], v[54:55], v[54:55]
	v_pk_mul_f32 v[48:49], v[48:49], v[48:49]
	v_pk_mul_f32 v[50:51], v[50:51], v[50:51]
	v_cvt_pk_bf16_f32 v59, v58, v59
	v_cvt_pk_bf16_f32 v58, v56, v57
	v_cvt_pk_bf16_f32 v56, v60, v61
	v_cvt_pk_bf16_f32 v57, v62, v63
	v_cvt_pk_bf16_f32 v51, v50, v51
	v_cvt_pk_bf16_f32 v50, v48, v49
	v_cvt_pk_bf16_f32 v48, v52, v53
	v_cvt_pk_bf16_f32 v49, v54, v55
	s_nop 1
	v_permlane16_swap_b32_e32 v56, v58
	v_permlane16_swap_b32_e32 v57, v59
	v_permlane16_swap_b32_e32 v48, v50
	v_permlane16_swap_b32_e32 v49, v51
	global_store_dwordx4 v[64:65], v[56:59], off
	global_store_dwordx4 v[64:65], v[48:51], off offset:256
	s_nop 1
	global_load_dword v50, v[140:141], off offset:576
	v_add_co_u32_e32 v52, vcc, s60, v142
	v_lshl_add_u64 v[48:49], v[142:143], 0, s[18:19]
	s_nop 0
	v_addc_co_u32_e32 v53, vcc, 0, v143, vcc
	s_waitcnt vmcnt(0)
; DI unsigned cvtpk(float lo, float hi) { f32x2_t v = {lo, hi}; bf16x2_t b = __builtin_convertvector(v, bf16x2_t); return __builtin_bit_cast(unsigned, b); }
; DI float frsq_(float x) { return __builtin_amdgcn_rsqf(x); }
;     DI void operator()(const f32x4 (&acc)[2][2][4][2], const Unit& u, int wr, int wc, int fr, int fq) const {
;         const int row0 = u.pm * BM + wr * 64 + fr, col0 = u.pn * BM + wc * 32 + 4 * fq;
; #pragma unroll
;         for (int ai = 0; ai < 2; ++ai)
; #pragma unroll
;             for (int m = 0; m < 4; ++m) { bf16_t* rp = O + (size_t)(row0 + ai * HALF + m * 16) * ldc + col0;
;                 float rsc = 1.f; if (RSCALE) rsc = frsq_(rss[row0 + ai * HALF + m * 16] * (1.f / 2048.f) + EPS);
; #pragma unroll
;                 for (int bj = 0; bj < 2; ++bj)
; #pragma unroll
;                     for (int n = 0; n < 2; ++n) { f32x4 v = acc[ai][bj][m][n]; if (RSCALE) v = v * rsc;
;                         if (ACT == 1) {
; #pragma unroll
;                             for (int j = 0; j < 4; ++j) { const float r = v[j] > 0.f ? v[j] : 0.f; v[j] = r * r; } }
;                         u32x2 w; w.x = cvtpk(v[0], v[1]); w.y = cvtpk(v[2], v[3]); *(u32x2*)(rp + bj * HALF + n * 16) = w; } }
;     }
	v_fmamk_f32 v50, v50, 0x3a000000, v154
	v_rsq_f32_e32 v50, v50
	s_nop 0
	v_pk_mul_f32 v[46:47], v[46:47], v[50:51] op_sel_hi:[1,0]
	v_pk_mul_f32 v[44:45], v[44:45], v[50:51] op_sel_hi:[1,0]
	v_pk_mul_f32 v[42:43], v[42:43], v[50:51] op_sel_hi:[1,0]
	v_pk_mul_f32 v[40:41], v[40:41], v[50:51] op_sel_hi:[1,0]
	v_pk_mul_f32 v[38:39], v[38:39], v[50:51] op_sel_hi:[1,0]
	v_pk_mul_f32 v[36:37], v[36:37], v[50:51] op_sel_hi:[1,0]
	v_pk_mul_f32 v[34:35], v[34:35], v[50:51] op_sel_hi:[1,0]
	v_pk_mul_f32 v[32:33], v[32:33], v[50:51] op_sel_hi:[1,0]
	v_max_f32_e32 v45, 0, v45
	v_max_f32_e32 v44, 0, v44
	v_max_f32_e32 v47, 0, v47
	v_max_f32_e32 v46, 0, v46
	v_max_f32_e32 v41, 0, v41
	v_max_f32_e32 v40, 0, v40
	v_max_f32_e32 v43, 0, v43
	v_max_f32_e32 v42, 0, v42
	v_max_f32_e32 v37, 0, v37
	v_max_f32_e32 v36, 0, v36
	v_max_f32_e32 v39, 0, v39
	v_max_f32_e32 v38, 0, v38
	v_max_f32_e32 v33, 0, v33
	v_max_f32_e32 v32, 0, v32
	v_max_f32_e32 v35, 0, v35
	v_max_f32_e32 v34, 0, v34
	v_pk_mul_f32 v[44:45], v[44:45], v[44:45]
	v_pk_mul_f32 v[46:47], v[46:47], v[46:47]
	v_pk_mul_f32 v[40:41], v[40:41], v[40:41]
	v_pk_mul_f32 v[42:43], v[42:43], v[42:43]
	v_pk_mul_f32 v[36:37], v[36:37], v[36:37]
	v_pk_mul_f32 v[38:39], v[38:39], v[38:39]
	v_pk_mul_f32 v[32:33], v[32:33], v[32:33]
	v_pk_mul_f32 v[34:35], v[34:35], v[34:35]
	v_cvt_pk_bf16_f32 v43, v42, v43
	v_cvt_pk_bf16_f32 v42, v40, v41
	v_cvt_pk_bf16_f32 v40, v44, v45
	v_cvt_pk_bf16_f32 v41, v46, v47
	v_cvt_pk_bf16_f32 v35, v34, v35
	v_cvt_pk_bf16_f32 v34, v32, v33
	v_cvt_pk_bf16_f32 v32, v36, v37
	v_cvt_pk_bf16_f32 v33, v38, v39
	s_nop 1
	v_permlane16_swap_b32_e32 v40, v42
	v_permlane16_swap_b32_e32 v41, v43
	v_permlane16_swap_b32_e32 v32, v34
	v_permlane16_swap_b32_e32 v33, v35
	global_store_dwordx4 v[48:49], v[40:43], off
	global_store_dwordx4 v[48:49], v[32:35], off offset:256
	s_nop 1
	global_load_dword v34, v[140:141], off offset:640
	v_add_co_u32_e32 v36, vcc, s61, v142
	v_lshl_add_u64 v[32:33], v[142:143], 0, s[20:21]
	s_nop 0
	v_addc_co_u32_e32 v37, vcc, 0, v143, vcc
	s_andn2_b64 vcc, exec, s[2:3]
	s_waitcnt vmcnt(0)
	v_fmamk_f32 v34, v34, 0x3a000000, v154
	v_rsq_f32_e32 v34, v34
	s_nop 0
	v_pk_mul_f32 v[30:31], v[30:31], v[34:35] op_sel_hi:[1,0]
	v_pk_mul_f32 v[28:29], v[28:29], v[34:35] op_sel_hi:[1,0]
	v_pk_mul_f32 v[26:27], v[26:27], v[34:35] op_sel_hi:[1,0]
	v_pk_mul_f32 v[24:25], v[24:25], v[34:35] op_sel_hi:[1,0]
	v_pk_mul_f32 v[22:23], v[22:23], v[34:35] op_sel_hi:[1,0]
	v_pk_mul_f32 v[20:21], v[20:21], v[34:35] op_sel_hi:[1,0]
	v_pk_mul_f32 v[18:19], v[18:19], v[34:35] op_sel_hi:[1,0]
	v_pk_mul_f32 v[16:17], v[16:17], v[34:35] op_sel_hi:[1,0]
	v_max_f32_e32 v29, 0, v29
	v_max_f32_e32 v28, 0, v28
	v_max_f32_e32 v31, 0, v31
	v_max_f32_e32 v30, 0, v30
	v_max_f32_e32 v25, 0, v25
	v_max_f32_e32 v24, 0, v24
	v_max_f32_e32 v27, 0, v27
	v_max_f32_e32 v26, 0, v26
	v_max_f32_e32 v21, 0, v21
	v_max_f32_e32 v20, 0, v20
	v_max_f32_e32 v23, 0, v23
	v_max_f32_e32 v22, 0, v22
	v_max_f32_e32 v17, 0, v17
	v_max_f32_e32 v16, 0, v16
	v_max_f32_e32 v19, 0, v19
	v_max_f32_e32 v18, 0, v18
	v_pk_mul_f32 v[28:29], v[28:29], v[28:29]
	v_pk_mul_f32 v[30:31], v[30:31], v[30:31]
	v_pk_mul_f32 v[24:25], v[24:25], v[24:25]
	v_pk_mul_f32 v[26:27], v[26:27], v[26:27]
	v_pk_mul_f32 v[20:21], v[20:21], v[20:21]
	v_pk_mul_f32 v[22:23], v[22:23], v[22:23]
	v_pk_mul_f32 v[16:17], v[16:17], v[16:17]
	v_pk_mul_f32 v[18:19], v[18:19], v[18:19]
	v_cvt_pk_bf16_f32 v27, v26, v27
	v_cvt_pk_bf16_f32 v26, v24, v25
	v_cvt_pk_bf16_f32 v24, v28, v29
	v_cvt_pk_bf16_f32 v25, v30, v31
	v_cvt_pk_bf16_f32 v19, v18, v19
	v_cvt_pk_bf16_f32 v18, v16, v17
	v_cvt_pk_bf16_f32 v16, v20, v21
	v_cvt_pk_bf16_f32 v17, v22, v23
	s_nop 1
	v_permlane16_swap_b32_e32 v24, v26
	v_permlane16_swap_b32_e32 v25, v27
	v_permlane16_swap_b32_e32 v16, v18
	v_permlane16_swap_b32_e32 v17, v19
	global_store_dwordx4 v[32:33], v[24:27], off
	global_store_dwordx4 v[32:33], v[16:19], off offset:256
	s_nop 1
	global_load_dword v18, v[140:141], off offset:704
	v_add_co_u32_e64 v20, s[0:1], s62, v142
	v_lshl_add_u64 v[16:17], v[142:143], 0, s[22:23]
	s_nop 0
	v_addc_co_u32_e64 v21, s[0:1], 0, v143, s[0:1]
	s_mov_b64 s[0:1], -1
	s_waitcnt vmcnt(0)
	v_fmamk_f32 v18, v18, 0x3a000000, v154
	v_rsq_f32_e32 v18, v18
	s_nop 0
	v_pk_mul_f32 v[14:15], v[14:15], v[18:19] op_sel_hi:[1,0]
	v_pk_mul_f32 v[12:13], v[12:13], v[18:19] op_sel_hi:[1,0]
	v_pk_mul_f32 v[10:11], v[10:11], v[18:19] op_sel_hi:[1,0]
	v_pk_mul_f32 v[8:9], v[8:9], v[18:19] op_sel_hi:[1,0]
	v_pk_mul_f32 v[6:7], v[6:7], v[18:19] op_sel_hi:[1,0]
	v_pk_mul_f32 v[4:5], v[4:5], v[18:19] op_sel_hi:[1,0]
	v_pk_mul_f32 v[2:3], v[2:3], v[18:19] op_sel_hi:[1,0]
	v_pk_mul_f32 v[0:1], v[0:1], v[18:19] op_sel_hi:[1,0]
	v_max_f32_e32 v13, 0, v13
	v_max_f32_e32 v12, 0, v12
	v_max_f32_e32 v15, 0, v15
	v_max_f32_e32 v14, 0, v14
	v_max_f32_e32 v9, 0, v9
	v_max_f32_e32 v8, 0, v8
	v_max_f32_e32 v11, 0, v11
	v_max_f32_e32 v10, 0, v10
	v_max_f32_e32 v5, 0, v5
	v_max_f32_e32 v4, 0, v4
	v_max_f32_e32 v7, 0, v7
	v_max_f32_e32 v6, 0, v6
	v_max_f32_e32 v1, 0, v1
	v_max_f32_e32 v0, 0, v0
	v_max_f32_e32 v3, 0, v3
	v_max_f32_e32 v2, 0, v2
	v_pk_mul_f32 v[12:13], v[12:13], v[12:13]
	v_pk_mul_f32 v[14:15], v[14:15], v[14:15]
	v_pk_mul_f32 v[8:9], v[8:9], v[8:9]
	v_pk_mul_f32 v[10:11], v[10:11], v[10:11]
	v_pk_mul_f32 v[4:5], v[4:5], v[4:5]
	v_pk_mul_f32 v[6:7], v[6:7], v[6:7]
	v_pk_mul_f32 v[0:1], v[0:1], v[0:1]
	v_pk_mul_f32 v[2:3], v[2:3], v[2:3]
	v_cvt_pk_bf16_f32 v11, v10, v11
	v_cvt_pk_bf16_f32 v10, v8, v9
	v_cvt_pk_bf16_f32 v8, v12, v13
	v_cvt_pk_bf16_f32 v9, v14, v15
	v_cvt_pk_bf16_f32 v3, v2, v3
	v_cvt_pk_bf16_f32 v2, v0, v1
	v_cvt_pk_bf16_f32 v0, v4, v5
	v_cvt_pk_bf16_f32 v1, v6, v7
	s_nop 1
	v_permlane16_swap_b32_e32 v8, v10
	v_permlane16_swap_b32_e32 v9, v11
	v_permlane16_swap_b32_e32 v0, v2
	v_permlane16_swap_b32_e32 v1, v3
	global_store_dwordx4 v[16:17], v[8:11], off
	global_store_dwordx4 v[16:17], v[0:3], off offset:256
	s_nop 1
	s_cbranch_vccnz .LBB0_1386
	s_andn2_b64 vcc, exec, s[6:7]
	s_cbranch_vccnz .LBB0_1385
	s_barrier
	s_branch .LBB0_1385
